# v82 + same ALIGN_EPI barrier-pair removal in the P1b block (normal, early and shed-unit calls)
# baseline (speedup 1.0000x reference)
.LBB0_556:
	ds_read_b128 v[128:131], v182
	ds_read_b128 v[132:135], v182 offset:1024
	ds_read_b128 v[136:139], v182 offset:2048
	ds_read_b128 v[140:143], v182 offset:3072
	ds_read_b128 v[164:167], v183
	ds_read_b128 v[168:171], v183 offset:1024
	ds_read_b128 v[172:175], v183 offset:2048
	ds_read_b128 v[186:189], v183 offset:3072
	s_add_u32 s22, s20, 0xfffc0080
	s_addc_u32 s23, s21, -1
	s_cmp_eq_u32 s50, 12
	s_cselect_b32 s25, s15, s23
	s_cselect_b32 s24, s46, s22
	s_cselect_b32 s23, s13, s49
	s_cselect_b32 s22, s47, s48
	v_lshl_add_u64 v[176:177], s[20:21], 0, v[156:157]
	s_add_i32 m0, s29, 0xc000
	ds_read_b128 v[190:193], v184
	ds_read_b128 v[194:197], v184 offset:1024
	ds_read_b128 v[198:201], v184 offset:2048
	ds_read_b128 v[202:205], v184 offset:3072
	ds_read_b128 v[206:209], v184 offset:4096
	ds_read_b128 v[210:213], v184 offset:5120
	ds_read_b128 v[214:217], v184 offset:6144
	ds_read_b128 v[218:221], v184 offset:7168
	global_load_lds_dwordx4 v[176:177], off
	v_lshl_add_u64 v[176:177], s[20:21], 0, v[158:159]
	s_add_i32 m0, s29, 0xe000
	s_nop 0
	global_load_lds_dwordx4 v[176:177], off
	s_waitcnt vmcnt(8)
	s_waitcnt lgkmcnt(0)
	s_barrier
	s_setprio 1
	s_waitcnt lgkmcnt(0)
	v_mfma_f32_16x16x32_bf16 v[124:127], v[128:131], v[190:193], v[124:127]
	v_mfma_f32_16x16x32_bf16 v[120:123], v[136:139], v[190:193], v[120:123]
	v_mfma_f32_16x16x32_bf16 v[112:115], v[128:131], v[198:201], v[112:115]
	v_mfma_f32_16x16x32_bf16 v[104:107], v[136:139], v[198:201], v[104:107]
	v_mfma_f32_16x16x32_bf16 v[92:95], v[128:131], v[206:209], v[92:95]
	v_mfma_f32_16x16x32_bf16 v[88:91], v[136:139], v[206:209], v[88:91]
	v_mfma_f32_16x16x32_bf16 v[76:79], v[128:131], v[214:217], v[76:79]
	v_mfma_f32_16x16x32_bf16 v[72:75], v[136:139], v[214:217], v[72:75]
	v_mfma_f32_16x16x32_bf16 v[124:127], v[132:135], v[194:197], v[124:127]
	v_mfma_f32_16x16x32_bf16 v[120:123], v[140:143], v[194:197], v[120:123]
	v_mfma_f32_16x16x32_bf16 v[112:115], v[132:135], v[202:205], v[112:115]
	v_mfma_f32_16x16x32_bf16 v[104:107], v[140:143], v[202:205], v[104:107]
	v_mfma_f32_16x16x32_bf16 v[92:95], v[132:135], v[210:213], v[92:95]
	v_mfma_f32_16x16x32_bf16 v[88:91], v[140:143], v[210:213], v[88:91]
	v_mfma_f32_16x16x32_bf16 v[76:79], v[132:135], v[218:221], v[76:79]
	v_mfma_f32_16x16x32_bf16 v[72:75], v[140:143], v[218:221], v[72:75]
	s_setprio 0
	s_setprio 1
	v_mfma_f32_16x16x32_bf16 v[116:119], v[164:167], v[190:193], v[116:119]
	v_mfma_f32_16x16x32_bf16 v[108:111], v[172:175], v[190:193], v[108:111]
	v_mfma_f32_16x16x32_bf16 v[100:103], v[164:167], v[198:201], v[100:103]
	v_mfma_f32_16x16x32_bf16 v[96:99], v[172:175], v[198:201], v[96:99]
	v_mfma_f32_16x16x32_bf16 v[84:87], v[164:167], v[206:209], v[84:87]
	v_mfma_f32_16x16x32_bf16 v[80:83], v[172:175], v[206:209], v[80:83]
	v_mfma_f32_16x16x32_bf16 v[68:71], v[164:167], v[214:217], v[68:71]
	v_mfma_f32_16x16x32_bf16 v[64:67], v[172:175], v[214:217], v[64:67]
	v_mfma_f32_16x16x32_bf16 v[116:119], v[168:171], v[194:197], v[116:119]
	v_mfma_f32_16x16x32_bf16 v[108:111], v[186:189], v[194:197], v[108:111]
	v_mfma_f32_16x16x32_bf16 v[100:103], v[168:171], v[202:205], v[100:103]
	v_mfma_f32_16x16x32_bf16 v[96:99], v[186:189], v[202:205], v[96:99]
	v_mfma_f32_16x16x32_bf16 v[84:87], v[168:171], v[210:213], v[84:87]
	v_mfma_f32_16x16x32_bf16 v[80:83], v[186:189], v[210:213], v[80:83]
	v_mfma_f32_16x16x32_bf16 v[68:71], v[168:171], v[218:221], v[68:71]
	v_mfma_f32_16x16x32_bf16 v[64:67], v[186:189], v[218:221], v[64:67]
	s_setprio 0
	s_barrier
	s_add_i32 s51, s40, s28
	v_lshl_add_u64 v[176:177], s[22:23], 0, v[148:149]
	s_mov_b32 m0, s51
	ds_read_b128 v[190:193], v184 offset:16384
	ds_read_b128 v[194:197], v184 offset:17408
	ds_read_b128 v[198:201], v184 offset:18432
	ds_read_b128 v[202:205], v184 offset:19456
	ds_read_b128 v[206:209], v184 offset:20480
	ds_read_b128 v[210:213], v184 offset:21504
	ds_read_b128 v[214:217], v184 offset:22528
	ds_read_b128 v[218:221], v184 offset:23552
	global_load_lds_dwordx4 v[176:177], off
	s_add_i32 m0, s51, 0x2000
	s_add_u32 s52, s22, 0x40000
	v_lshl_add_u64 v[222:223], s[22:23], 0, v[144:145]
	s_addc_u32 s53, s23, 0
	s_add_i32 s51, s41, s28
	global_load_lds_dwordx4 v[222:223], off
	v_lshl_add_u64 v[224:225], s[52:53], 0, v[148:149]
	s_mov_b32 m0, s51
	v_lshl_add_u64 v[226:227], s[24:25], 0, v[146:147]
	global_load_lds_dwordx4 v[224:225], off
	v_lshl_add_u64 v[224:225], s[52:53], 0, v[144:145]
	s_add_i32 m0, s51, 0x2000
	s_nop 0
	global_load_lds_dwordx4 v[224:225], off
	v_lshl_add_u64 v[224:225], s[24:25], 0, v[150:151]
	s_mov_b32 m0, s29
	s_nop 0
	global_load_lds_dwordx4 v[224:225], off
	s_mov_b32 m0, s30
	s_nop 0
	global_load_lds_dwordx4 v[226:227], off
	s_waitcnt vmcnt(8)
	s_waitcnt lgkmcnt(0)
	s_barrier
	s_setprio 1
	s_waitcnt lgkmcnt(0)
	v_mfma_f32_16x16x32_bf16 v[60:63], v[128:131], v[190:193], v[60:63]
	v_mfma_f32_16x16x32_bf16 v[56:59], v[136:139], v[190:193], v[56:59]
	v_mfma_f32_16x16x32_bf16 v[48:51], v[128:131], v[198:201], v[48:51]
	v_mfma_f32_16x16x32_bf16 v[40:43], v[136:139], v[198:201], v[40:43]
	v_mfma_f32_16x16x32_bf16 v[32:35], v[128:131], v[206:209], v[32:35]
	v_mfma_f32_16x16x32_bf16 v[24:27], v[136:139], v[206:209], v[24:27]
	v_mfma_f32_16x16x32_bf16 v[16:19], v[128:131], v[214:217], v[16:19]
	v_mfma_f32_16x16x32_bf16 v[8:11], v[136:139], v[214:217], v[8:11]
	v_mfma_f32_16x16x32_bf16 v[60:63], v[132:135], v[194:197], v[60:63]
	v_mfma_f32_16x16x32_bf16 v[56:59], v[140:143], v[194:197], v[56:59]
	v_mfma_f32_16x16x32_bf16 v[48:51], v[132:135], v[202:205], v[48:51]
	v_mfma_f32_16x16x32_bf16 v[40:43], v[140:143], v[202:205], v[40:43]
	v_mfma_f32_16x16x32_bf16 v[32:35], v[132:135], v[210:213], v[32:35]
	v_mfma_f32_16x16x32_bf16 v[24:27], v[140:143], v[210:213], v[24:27]
	v_mfma_f32_16x16x32_bf16 v[16:19], v[132:135], v[218:221], v[16:19]
	v_mfma_f32_16x16x32_bf16 v[8:11], v[140:143], v[218:221], v[8:11]
	s_setprio 0
	s_setprio 1
	v_mfma_f32_16x16x32_bf16 v[52:55], v[164:167], v[190:193], v[52:55]
	v_mfma_f32_16x16x32_bf16 v[44:47], v[172:175], v[190:193], v[44:47]
	v_mfma_f32_16x16x32_bf16 v[36:39], v[164:167], v[198:201], v[36:39]
	v_mfma_f32_16x16x32_bf16 v[28:31], v[172:175], v[198:201], v[28:31]
	v_mfma_f32_16x16x32_bf16 v[20:23], v[164:167], v[206:209], v[20:23]
	v_mfma_f32_16x16x32_bf16 v[12:15], v[172:175], v[206:209], v[12:15]
	v_mfma_f32_16x16x32_bf16 v[4:7], v[164:167], v[214:217], v[4:7]
	v_mfma_f32_16x16x32_bf16 v[0:3], v[172:175], v[214:217], v[0:3]
	v_mfma_f32_16x16x32_bf16 v[52:55], v[168:171], v[194:197], v[52:55]
	v_mfma_f32_16x16x32_bf16 v[44:47], v[186:189], v[194:197], v[44:47]
	v_mfma_f32_16x16x32_bf16 v[36:39], v[168:171], v[202:205], v[36:39]
	v_mfma_f32_16x16x32_bf16 v[28:31], v[186:189], v[202:205], v[28:31]
	v_mfma_f32_16x16x32_bf16 v[20:23], v[168:171], v[210:213], v[20:23]
	v_mfma_f32_16x16x32_bf16 v[12:15], v[186:189], v[210:213], v[12:15]
	v_mfma_f32_16x16x32_bf16 v[4:7], v[168:171], v[218:221], v[4:7]
	v_mfma_f32_16x16x32_bf16 v[0:3], v[186:189], v[218:221], v[0:3]
	s_setprio 0
	s_barrier
	s_add_i32 s51, 0, 0x18000
	s_add_i32 s52, 0, 0x1c000
	v_add_u32_e32 v140, s51, v180
	v_add_u32_e32 v152, s52, v180
	ds_read_b128 v[128:131], v140
	ds_read_b128 v[132:135], v140 offset:1024
	ds_read_b128 v[136:139], v140 offset:2048
	ds_read_b128 v[140:143], v140 offset:3072
	ds_read_b128 v[164:167], v152
	ds_read_b128 v[168:171], v152 offset:1024
	ds_read_b128 v[172:175], v152 offset:2048
	ds_read_b128 v[186:189], v152 offset:3072
	s_add_u32 s24, s24, 0x40000
	s_addc_u32 s25, s25, 0
	s_mov_b32 m0, s31
	v_lshl_add_u64 v[228:229], s[24:25], 0, v[150:151]
	ds_read_b128 v[190:193], v184 offset:32768
	ds_read_b128 v[194:197], v184 offset:33792
	ds_read_b128 v[198:201], v184 offset:34816
	ds_read_b128 v[202:205], v184 offset:35840
	ds_read_b128 v[206:209], v184 offset:36864
	ds_read_b128 v[210:213], v184 offset:37888
	ds_read_b128 v[214:217], v184 offset:38912
	ds_read_b128 v[218:221], v184 offset:39936
	global_load_lds_dwordx4 v[228:229], off
	v_lshl_add_u64 v[228:229], s[24:25], 0, v[146:147]
	s_mov_b32 m0, s34
	s_nop 0
	global_load_lds_dwordx4 v[228:229], off
	s_waitcnt vmcnt(8)
	s_waitcnt lgkmcnt(0)
	s_barrier
	s_setprio 1
	s_waitcnt lgkmcnt(0)
	v_mfma_f32_16x16x32_bf16 v[124:127], v[128:131], v[190:193], v[124:127]
	v_mfma_f32_16x16x32_bf16 v[120:123], v[136:139], v[190:193], v[120:123]
	v_mfma_f32_16x16x32_bf16 v[112:115], v[128:131], v[198:201], v[112:115]
	v_mfma_f32_16x16x32_bf16 v[104:107], v[136:139], v[198:201], v[104:107]
	v_mfma_f32_16x16x32_bf16 v[92:95], v[128:131], v[206:209], v[92:95]
	v_mfma_f32_16x16x32_bf16 v[88:91], v[136:139], v[206:209], v[88:91]
	v_mfma_f32_16x16x32_bf16 v[76:79], v[128:131], v[214:217], v[76:79]
	v_mfma_f32_16x16x32_bf16 v[72:75], v[136:139], v[214:217], v[72:75]
	v_mfma_f32_16x16x32_bf16 v[124:127], v[132:135], v[194:197], v[124:127]
	v_mfma_f32_16x16x32_bf16 v[120:123], v[140:143], v[194:197], v[120:123]
	v_mfma_f32_16x16x32_bf16 v[112:115], v[132:135], v[202:205], v[112:115]
	v_mfma_f32_16x16x32_bf16 v[104:107], v[140:143], v[202:205], v[104:107]
	v_mfma_f32_16x16x32_bf16 v[92:95], v[132:135], v[210:213], v[92:95]
	v_mfma_f32_16x16x32_bf16 v[88:91], v[140:143], v[210:213], v[88:91]
	v_mfma_f32_16x16x32_bf16 v[76:79], v[132:135], v[218:221], v[76:79]
	v_mfma_f32_16x16x32_bf16 v[72:75], v[140:143], v[218:221], v[72:75]
	s_setprio 0
	s_setprio 1
	v_mfma_f32_16x16x32_bf16 v[116:119], v[164:167], v[190:193], v[116:119]
	v_mfma_f32_16x16x32_bf16 v[108:111], v[172:175], v[190:193], v[108:111]
	v_mfma_f32_16x16x32_bf16 v[100:103], v[164:167], v[198:201], v[100:103]
	v_mfma_f32_16x16x32_bf16 v[96:99], v[172:175], v[198:201], v[96:99]
	v_mfma_f32_16x16x32_bf16 v[84:87], v[164:167], v[206:209], v[84:87]
	v_mfma_f32_16x16x32_bf16 v[80:83], v[172:175], v[206:209], v[80:83]
	v_mfma_f32_16x16x32_bf16 v[68:71], v[164:167], v[214:217], v[68:71]
	v_mfma_f32_16x16x32_bf16 v[64:67], v[172:175], v[214:217], v[64:67]
	v_mfma_f32_16x16x32_bf16 v[116:119], v[168:171], v[194:197], v[116:119]
	v_mfma_f32_16x16x32_bf16 v[108:111], v[186:189], v[194:197], v[108:111]
	v_mfma_f32_16x16x32_bf16 v[100:103], v[168:171], v[202:205], v[100:103]
	v_mfma_f32_16x16x32_bf16 v[96:99], v[186:189], v[202:205], v[96:99]
	v_mfma_f32_16x16x32_bf16 v[84:87], v[168:171], v[210:213], v[84:87]
	v_mfma_f32_16x16x32_bf16 v[80:83], v[186:189], v[210:213], v[80:83]
	v_mfma_f32_16x16x32_bf16 v[68:71], v[168:171], v[218:221], v[68:71]
	v_mfma_f32_16x16x32_bf16 v[64:67], v[186:189], v[218:221], v[64:67]
	s_setprio 0
	s_barrier
	s_add_i32 s24, s51, s28
	v_lshl_add_u64 v[176:177], v[176:177], 0, s[6:7]
	s_mov_b32 m0, s24
	ds_read_b128 v[190:193], v184 offset:49152
	ds_read_b128 v[194:197], v184 offset:50176
	ds_read_b128 v[198:201], v184 offset:51200
	ds_read_b128 v[202:205], v184 offset:52224
	ds_read_b128 v[206:209], v184 offset:53248
	ds_read_b128 v[210:213], v184 offset:54272
	ds_read_b128 v[214:217], v184 offset:55296
	ds_read_b128 v[218:221], v184 offset:56320
	global_load_lds_dwordx4 v[176:177], off
	s_add_i32 m0, s24, 0x2000
	s_add_u32 s22, s22, 0x40080
	v_lshl_add_u64 v[176:177], v[222:223], 0, s[6:7]
	s_addc_u32 s23, s23, 0
	s_add_i32 s24, s52, s28
	global_load_lds_dwordx4 v[176:177], off
	v_lshl_add_u64 v[176:177], s[22:23], 0, v[148:149]
	s_mov_b32 m0, s24
	s_nop 0
	global_load_lds_dwordx4 v[176:177], off
	v_lshl_add_u64 v[176:177], s[22:23], 0, v[144:145]
	s_add_i32 m0, s24, 0x2000
	s_nop 0
	global_load_lds_dwordx4 v[176:177], off
	v_lshl_add_u64 v[176:177], v[224:225], 0, s[6:7]
	s_mov_b32 m0, s36
	s_nop 0
	global_load_lds_dwordx4 v[176:177], off
	v_lshl_add_u64 v[176:177], v[226:227], 0, s[6:7]
	s_mov_b32 m0, s37
	s_nop 0
	global_load_lds_dwordx4 v[176:177], off
	s_waitcnt vmcnt(8)
	s_waitcnt lgkmcnt(0)
	s_barrier
	s_setprio 1
	s_waitcnt lgkmcnt(0)
	v_mfma_f32_16x16x32_bf16 v[60:63], v[128:131], v[190:193], v[60:63]
	v_mfma_f32_16x16x32_bf16 v[56:59], v[136:139], v[190:193], v[56:59]
	v_mfma_f32_16x16x32_bf16 v[48:51], v[128:131], v[198:201], v[48:51]
	v_mfma_f32_16x16x32_bf16 v[40:43], v[136:139], v[198:201], v[40:43]
	v_mfma_f32_16x16x32_bf16 v[32:35], v[128:131], v[206:209], v[32:35]
	v_mfma_f32_16x16x32_bf16 v[24:27], v[136:139], v[206:209], v[24:27]
	v_mfma_f32_16x16x32_bf16 v[16:19], v[128:131], v[214:217], v[16:19]
	v_mfma_f32_16x16x32_bf16 v[8:11], v[136:139], v[214:217], v[8:11]
	v_mfma_f32_16x16x32_bf16 v[60:63], v[132:135], v[194:197], v[60:63]
	v_mfma_f32_16x16x32_bf16 v[56:59], v[140:143], v[194:197], v[56:59]
	v_mfma_f32_16x16x32_bf16 v[48:51], v[132:135], v[202:205], v[48:51]
	v_mfma_f32_16x16x32_bf16 v[40:43], v[140:143], v[202:205], v[40:43]
	v_mfma_f32_16x16x32_bf16 v[32:35], v[132:135], v[210:213], v[32:35]
	v_mfma_f32_16x16x32_bf16 v[24:27], v[140:143], v[210:213], v[24:27]
	v_mfma_f32_16x16x32_bf16 v[16:19], v[132:135], v[218:221], v[16:19]
	v_mfma_f32_16x16x32_bf16 v[8:11], v[140:143], v[218:221], v[8:11]
	s_setprio 0
	s_setprio 1
	v_mfma_f32_16x16x32_bf16 v[52:55], v[164:167], v[190:193], v[52:55]
	v_mfma_f32_16x16x32_bf16 v[44:47], v[172:175], v[190:193], v[44:47]
	v_mfma_f32_16x16x32_bf16 v[36:39], v[164:167], v[198:201], v[36:39]
	v_mfma_f32_16x16x32_bf16 v[28:31], v[172:175], v[198:201], v[28:31]
	v_mfma_f32_16x16x32_bf16 v[20:23], v[164:167], v[206:209], v[20:23]
	v_mfma_f32_16x16x32_bf16 v[12:15], v[172:175], v[206:209], v[12:15]
	v_mfma_f32_16x16x32_bf16 v[4:7], v[164:167], v[214:217], v[4:7]
	v_mfma_f32_16x16x32_bf16 v[0:3], v[172:175], v[214:217], v[0:3]
	v_mfma_f32_16x16x32_bf16 v[52:55], v[168:171], v[194:197], v[52:55]
	v_mfma_f32_16x16x32_bf16 v[44:47], v[186:189], v[194:197], v[44:47]
	v_mfma_f32_16x16x32_bf16 v[36:39], v[168:171], v[202:205], v[36:39]
	v_mfma_f32_16x16x32_bf16 v[28:31], v[186:189], v[202:205], v[28:31]
	v_mfma_f32_16x16x32_bf16 v[20:23], v[168:171], v[210:213], v[20:23]
	v_mfma_f32_16x16x32_bf16 v[12:15], v[186:189], v[210:213], v[12:15]
	v_mfma_f32_16x16x32_bf16 v[4:7], v[168:171], v[218:221], v[4:7]
	v_mfma_f32_16x16x32_bf16 v[0:3], v[186:189], v[218:221], v[0:3]
	s_setprio 0
	s_barrier
	s_add_i32 s50, s50, 2
	s_add_u32 s20, s20, 0x100
	s_addc_u32 s21, s21, 0
	s_add_u32 s48, s48, 0x100
	s_addc_u32 s49, s49, 0
	s_cmp_gt_u32 s50, 13
	s_cbranch_scc0 .LBB0_556
	s_and_b64 vcc, exec, s[8:9]
	s_cbranch_vccz .LBB0_559
	s_and_b64 vcc, exec, s[2:3]
	s_cbranch_vccnz .LBB0_559
	s_barrier

.LBB0_564:
	s_andn2_b64 vcc, exec, s[0:1]
	s_cbranch_vccnz .LBB0_551
	s_branch .LBB0_551
